# LRU: conv taps/bias loaded and packed to f16 once per item instead of every chunk
# baseline (speedup 1.0000x reference)
.LBB0_359:
	s_bfe_u32 s25, s11, 0x20003
	s_lshl_b32 s3, s25, 5
	s_or_b32 s1, s0, s3
	v_or_b32_e32 v2, s1, v116
	v_lshlrev_b32_e32 v8, 2, v2
	v_add_u32_e32 v0, s1, v79
	global_load_dword v10, v8, s[60:61]
	v_ashrrev_i32_e32 v1, 31, v0
	v_lshlrev_b64 v[0:1], 8, v[0:1]
	v_lshl_or_b32 v0, v78, 1, v0
	v_lshl_add_u64 v[2:3], s[42:43], 0, v[0:1]
	v_lshl_add_u64 v[4:5], s[44:45], 0, v[0:1]
	global_load_dwordx4 v[0:3], v[2:3], off
	s_nop 0
	global_load_dwordx4 v[4:7], v[4:5], off
	s_lshl_b32 s1, s11, 7
	s_and_b32 s18, s1, 0xfffff000
	s_ashr_i32 s19, s18, 31
	s_lshl_b64 s[22:23], s[18:19], 11
	s_add_u32 s1, s57, s22
	s_addc_u32 s16, s63, s23
	s_lshl_b32 s0, s0, 1
	s_add_u32 s20, s1, s0
	s_addc_u32 s21, s16, 0
	global_load_dword v12, v8, s[54:55]
	global_load_dword v13, v8, s[58:59]
	v_lshl_add_u64 v[8:9], s[20:21], 0, v[82:83]
	v_lshl_add_u64 v[20:21], s[20:21], 0, v[84:85]
	v_lshl_add_u64 v[24:25], s[20:21], 0, v[86:87]
	v_lshl_add_u64 v[28:29], s[20:21], 0, v[88:89]
	v_lshl_add_u64 v[32:33], s[20:21], 0, v[90:91]
	v_lshl_add_u64 v[34:35], s[20:21], 0, v[92:93]
	v_lshl_add_u64 v[36:37], s[20:21], 0, v[94:95]
	v_lshl_add_u64 v[38:39], s[20:21], 0, v[96:97]
	v_lshl_add_u64 v[40:41], s[20:21], 0, v[98:99]
	v_lshl_add_u64 v[42:43], s[20:21], 0, v[100:101]
	global_load_dwordx4 v[16:19], v[8:9], off
	s_nop 0
	global_load_dwordx4 v[20:23], v[20:21], off
	s_nop 0
	global_load_dwordx4 v[24:27], v[24:25], off
	s_nop 0
	global_load_dwordx4 v[28:31], v[28:29], off
	s_nop 0
	global_load_dwordx4 v[48:51], v[32:33], off
	global_load_dwordx4 v[52:55], v[34:35], off
	global_load_dwordx4 v[56:59], v[36:37], off
	global_load_dwordx4 v[60:63], v[38:39], off
	global_load_dwordx4 v[64:67], v[40:41], off
	global_load_dwordx4 v[68:71], v[42:43], off
	v_lshl_add_u64 v[44:45], s[20:21], 0, v[102:103]
	v_add_u32_e32 v14, 0x22a00, v124
	v_add_u32_e32 v15, 0x24a00, v124
	s_add_u32 s1, s65, s22
	s_mov_b32 s24, 0
	s_waitcnt vmcnt(14)
	v_mul_f32_e32 v8, 0xbfb8aa3b, v10
	v_exp_f32_e32 v36, v8
	global_load_dwordx4 v[8:11], v[44:45], off
	s_waitcnt vmcnt(14)
	ds_write_b128 v14, v[0:3]
	s_waitcnt vmcnt(13)
	ds_write_b128 v15, v[4:7]
	v_add_f32_e32 v2, 1.0, v36
	v_add_f32_e32 v3, -1.0, v2
	v_frexp_mant_f32_e32 v4, v2
	v_cvt_f64_f32_e32 v[0:1], v2
	v_sub_f32_e32 v5, v3, v2
	v_frexp_exp_i32_f64_e32 v0, v[0:1]
	v_cmp_gt_f32_e64 s[16:17], s94, v4
	v_sub_f32_e32 v3, v36, v3
	v_add_f32_e32 v1, 1.0, v5
	v_subbrev_co_u32_e64 v0, s[16:17], 0, v0, s[16:17]
	v_add_f32_e32 v1, v3, v1
	v_sub_u32_e32 v3, 0, v0
	v_ldexp_f32 v2, v2, v3
	v_add_f32_e32 v4, -1.0, v2
	v_add_f32_e32 v5, 1.0, v2
	v_ldexp_f32 v1, v1, v3
	v_add_f32_e32 v3, 1.0, v4
	v_add_f32_e32 v6, -1.0, v5
	v_sub_f32_e32 v3, v2, v3
	v_sub_f32_e32 v2, v2, v6
	v_add_f32_e32 v6, v1, v3
	v_add_f32_e32 v1, v1, v2
	v_add_f32_e32 v14, v5, v1
	v_rcp_f32_e32 v15, v14
	v_add_f32_e32 v3, v4, v6
	v_sub_f32_e32 v4, v3, v4
	v_sub_f32_e32 v2, v14, v5
	v_mul_f32_e32 v33, v3, v15
	v_sub_f32_e32 v32, v6, v4
	v_mul_f32_e32 v4, v14, v33
	v_sub_f32_e32 v1, v1, v2
	v_fma_f32 v6, v33, v14, -v4
	v_fmac_f32_e32 v6, v33, v1
	v_add_f32_e32 v2, v4, v6
	v_sub_f32_e32 v5, v3, v2
	v_mov_b32_e32 v7, v2
	v_pk_add_f32 v[2:3], v[2:3], v[4:5] neg_lo:[0,1] neg_hi:[0,1]
	v_cvt_f32_i32_e32 v0, v0
	v_pk_add_f32 v[2:3], v[2:3], v[6:7] neg_lo:[0,1] neg_hi:[0,1]
	v_cmp_neq_f32_e64 s[16:17], s96, v36
	v_add_f32_e32 v3, v32, v3
	v_add_f32_e32 v2, v2, v3
	v_add_f32_e32 v3, v5, v2
	v_mul_f32_e32 v7, v15, v3
	v_mul_f32_e32 v4, v14, v7
	v_sub_f32_e32 v5, v5, v3
	v_add_f32_e32 v34, v33, v7
	v_fma_f32 v6, v7, v14, -v4
	v_add_f32_e32 v32, v2, v5
	v_sub_f32_e32 v2, v34, v33
	v_fmac_f32_e32 v6, v7, v1
	v_sub_f32_e32 v1, v7, v2
	v_add_f32_e32 v2, v4, v6
	v_sub_f32_e32 v5, v3, v2
	v_mov_b32_e32 v7, v2
	v_pk_add_f32 v[2:3], v[2:3], v[4:5] neg_lo:[0,1] neg_hi:[0,1]
	s_waitcnt vmcnt(12)
	v_mul_f32_e32 v108, 0xbfb8aa3b, v12
	v_pk_add_f32 v[2:3], v[2:3], v[6:7] neg_lo:[0,1] neg_hi:[0,1]
	s_waitcnt vmcnt(11)
	v_mul_f32_e32 v110, 0xbfb8aa3b, v13
	v_add_f32_e32 v3, v32, v3
	v_add_f32_e32 v2, v2, v3
	v_add_f32_e32 v2, v5, v2
	v_mul_f32_e32 v2, v15, v2
	v_add_f32_e32 v1, v1, v2
	v_add_f32_e32 v2, v34, v1
	v_mul_f32_e32 v4, v2, v2
	v_sub_f32_e32 v5, v2, v34
	v_fmamk_f32 v6, v4, 0x3e9b6dac, v125
	v_sub_f32_e32 v5, v1, v5
	v_mul_f32_e32 v1, v2, v4
	v_fmaak_f32 v105, v4, v6, 0x3f2aaada
	v_ldexp_f32 v7, v5, 1
	v_pk_mul_f32 v[4:5], v[0:1], v[104:105]
	v_ldexp_f32 v3, v2, 1
	v_fma_f32 v2, v0, s95, -v4
	v_fmac_f32_e32 v2, 0xb102e308, v0
	v_pk_add_f32 v[0:1], v[4:5], v[2:3]
	v_mov_b32_e32 v6, v4
	v_sub_f32_e32 v32, v1, v3
	v_pk_add_f32 v[14:15], v[0:1], v[4:5] neg_lo:[0,1] neg_hi:[0,1]
	v_sub_f32_e32 v4, v5, v32
	v_add_f32_e32 v7, v7, v4
	v_pk_add_f32 v[4:5], v[0:1], v[6:7]
	v_mov_b32_e32 v3, v0
	v_mov_b32_e32 v15, v5
	v_pk_add_f32 v[34:35], v[2:3], v[14:15] neg_lo:[0,1] neg_hi:[0,1]
	v_pk_add_f32 v[2:3], v[2:3], v[14:15]
	v_mov_b32_e32 v32, v5
	v_pk_add_f32 v[14:15], v[2:3], v[0:1] op_sel:[1,0] op_sel_hi:[0,1] neg_lo:[0,1] neg_hi:[0,1]
	v_mov_b32_e32 v33, v3
	v_pk_add_f32 v[4:5], v[4:5], v[14:15] op_sel_hi:[1,0] neg_lo:[0,1] neg_hi:[0,1]
	v_pk_mov_b32 v[14:15], v[0:1], v[14:15] op_sel:[1,0]
	v_mov_b32_e32 v6, v7
	v_pk_add_f32 v[14:15], v[32:33], v[14:15] neg_lo:[0,1] neg_hi:[0,1]
	v_mov_b32_e32 v7, v0
	v_pk_add_f32 v[0:1], v[6:7], v[14:15] neg_lo:[0,1] neg_hi:[0,1]
	v_mov_b32_e32 v4, v34
	v_pk_add_f32 v[4:5], v[4:5], v[0:1]
	v_mov_b32_e32 v35, v3
	v_pk_add_f32 v[6:7], v[4:5], v[4:5] op_sel:[0,1] op_sel_hi:[1,0]
	s_waitcnt vmcnt(10)
	v_cndmask_b32_e64 v33, v17, 0, s[4:5]
	v_pk_add_f32 v[2:3], v[2:3], v[6:7] op_sel:[1,0] op_sel_hi:[0,1]
	v_mov_b32_e32 v5, v2
	v_pk_add_f32 v[14:15], v[4:5], v[34:35] neg_lo:[0,1] neg_hi:[0,1]
	v_mov_b32_e32 v1, v6
	v_sub_f32_e32 v3, v4, v14
	v_pk_add_f32 v[0:1], v[0:1], v[14:15] neg_lo:[0,1] neg_hi:[0,1]
	v_sub_f32_e32 v3, v34, v3
	v_add_f32_e32 v0, v0, v3
	v_add_f32_e32 v0, v0, v1
	v_add_f32_e32 v0, v2, v0
	v_cndmask_b32_e64 v0, v127, v0, s[16:17]
	v_cmp_ngt_f32_e64 s[16:17], -1.0, v36
	v_cndmask_b32_e64 v35, v19, 0, s[4:5]
	v_cndmask_b32_e64 v34, v18, 0, s[4:5]
	v_cndmask_b32_e64 v0, v128, v0, s[16:17]
	v_cmp_neq_f32_e64 s[16:17], -1.0, v36
	v_cndmask_b32_e64 v32, v16, 0, s[4:5]
	s_waitcnt vmcnt(9)
	v_cndmask_b32_e64 v39, v23, 0, s[4:5]
	v_cndmask_b32_e64 v0, v129, v0, s[16:17]
	v_cmp_lt_f32_e64 s[16:17], |v36|, s97
	v_cndmask_b32_e64 v38, v22, 0, s[4:5]
	v_cndmask_b32_e64 v37, v21, 0, s[4:5]
	v_cndmask_b32_e64 v0, v0, v36, s[16:17]
	s_addc_u32 s16, s67, s23
	s_add_u32 s0, s1, s0
	s_addc_u32 s1, s16, 0
	s_lshl_b32 s16, s25, 6
	s_add_u32 s22, s0, s16
	s_addc_u32 s23, s1, 0
	s_lshl_b64 s[0:1], s[18:19], 2
	s_add_u32 s0, s30, s0
	s_addc_u32 s1, s31, s1
	s_lshl_b32 s16, s52, 19
	s_lshl_b32 s17, s25, 17
	v_mul_f32_e32 v0, 0x41000000, v0
	s_or_b32 s16, s17, s16
	v_mul_f32_e32 v106, 0xbfb8aa3b, v0
	v_mul_f32_e32 v112, -2.0, v0
	s_add_u32 s25, s0, s16
	v_cndmask_b32_e64 v36, v20, 0, s[4:5]
	s_waitcnt vmcnt(8)
	v_cndmask_b32_e64 v43, v27, 0, s[4:5]
	v_cndmask_b32_e64 v42, v26, 0, s[4:5]
	v_cndmask_b32_e64 v41, v25, 0, s[4:5]
	v_cndmask_b32_e64 v40, v24, 0, s[4:5]
	s_waitcnt vmcnt(7)
	v_cndmask_b32_e64 v47, v31, 0, s[6:7]
	v_cndmask_b32_e64 v46, v30, 0, s[6:7]
	v_cndmask_b32_e64 v45, v29, 0, s[6:7]
	v_cndmask_b32_e64 v44, v28, 0, s[6:7]
	s_waitcnt vmcnt(6)
	v_cndmask_b32_e64 v51, v51, 0, s[6:7]
	v_cndmask_b32_e64 v50, v50, 0, s[6:7]
	v_cndmask_b32_e64 v49, v49, 0, s[6:7]
	v_cndmask_b32_e64 v48, v48, 0, s[6:7]
	s_waitcnt vmcnt(5)
	v_cndmask_b32_e64 v55, v55, 0, s[6:7]
	v_cndmask_b32_e64 v54, v54, 0, s[6:7]
	v_cndmask_b32_e64 v53, v53, 0, s[6:7]
	v_cndmask_b32_e64 v52, v52, 0, s[6:7]
	s_waitcnt vmcnt(4)
	v_cndmask_b32_e64 v59, v59, 0, s[6:7]
	v_cndmask_b32_e64 v58, v58, 0, s[6:7]
	v_cndmask_b32_e64 v57, v57, 0, s[6:7]
	v_cndmask_b32_e64 v56, v56, 0, s[6:7]
	s_waitcnt vmcnt(3)
	v_cndmask_b32_e64 v63, v63, 0, s[6:7]
	v_cndmask_b32_e64 v62, v62, 0, s[6:7]
	v_cndmask_b32_e64 v61, v61, 0, s[6:7]
	v_cndmask_b32_e64 v60, v60, 0, s[6:7]
	s_waitcnt vmcnt(2)
	v_cndmask_b32_e64 v67, v67, 0, s[6:7]
	v_cndmask_b32_e64 v66, v66, 0, s[6:7]
	v_cndmask_b32_e64 v65, v65, 0, s[6:7]
	v_cndmask_b32_e64 v64, v64, 0, s[6:7]
	s_waitcnt vmcnt(1)
	v_cndmask_b32_e64 v71, v71, 0, s[6:7]
	v_cndmask_b32_e64 v70, v70, 0, s[6:7]
	v_cndmask_b32_e64 v69, v69, 0, s[6:7]
	v_cndmask_b32_e64 v68, v68, 0, s[6:7]
	s_waitcnt vmcnt(0)
	v_cndmask_b32_e64 v75, v11, 0, s[6:7]
	v_cndmask_b32_e64 v74, v10, 0, s[6:7]
	v_cndmask_b32_e64 v73, v9, 0, s[6:7]
	v_cndmask_b32_e64 v72, v8, 0, s[6:7]
	v_mov_b32_e32 v109, v108
	v_mov_b32_e32 v111, v110
	v_mov_b32_e32 v107, v106
	v_mov_b32_e32 v113, v112
	s_addc_u32 s26, s1, 0
	v_mov_b32_e32 v105, 0
	v_add_u32_e32 v200, 0x22000, v121
	ds_write_b32 v200, v202
	v_cmp_gt_u32_e32 vcc, 0x80, v76
	s_and_saveexec_b64 s[16:17], vcc
	ds_write_b32 v200, v203 offset:2048
	s_or_b64 exec, exec, s[16:17]
	s_waitcnt lgkmcnt(0)
	v_bfe_u32 v234, v76, 5, 1
	v_bfe_u32 v235, v116, 3, 1
	v_and_b32_e32 v236, 1, v116
	v_lshlrev_b32_e32 v236, 4, v236
	v_mov_b32_e32 v237, 0x3c00
	v_cmp_eq_u32_e32 vcc, v234, v235
	v_lshlrev_b32_e32 v237, v236, v237
	s_nop 1
	v_cndmask_b32_e32 v237, 0, v237, vcc
	v_bfe_u32 v238, v116, 1, 2
	v_cmp_gt_u32_e64 s[16:17], 16, v116
	v_cmp_eq_u32_e32 vcc, 0, v238
	s_nop 1
	v_cndmask_b32_e32 v239, 0, v237, vcc
	s_nop 0
	v_cndmask_b32_e64 v168, 0, v239, s[16:17]
	v_cndmask_b32_e64 v172, v239, 0, s[16:17]
	v_cmp_eq_u32_e32 vcc, 1, v238
	s_nop 1
	v_cndmask_b32_e32 v239, 0, v237, vcc
	s_nop 0
	v_cndmask_b32_e64 v169, 0, v239, s[16:17]
	v_cndmask_b32_e64 v173, v239, 0, s[16:17]
	v_cmp_eq_u32_e32 vcc, 2, v238
	s_nop 1
	v_cndmask_b32_e32 v239, 0, v237, vcc
	s_nop 0
	v_cndmask_b32_e64 v170, 0, v239, s[16:17]
	v_cndmask_b32_e64 v174, v239, 0, s[16:17]
	v_cmp_eq_u32_e32 vcc, 3, v238
	s_nop 1
	v_cndmask_b32_e32 v239, 0, v237, vcc
	s_nop 0
	v_cndmask_b32_e64 v171, 0, v239, s[16:17]
	v_cndmask_b32_e64 v175, v239, 0, s[16:17]
	v_bfe_u32 v80, v76, 5, 1
	v_lshlrev_b32_e32 v132, 4, v76
	v_and_b32_e32 v132, 0x70, v132
	v_lshlrev_b32_e32 v80, 4, v80
	v_lshlrev_b32_e32 v133, 8, v116
	v_or_b32_e32 v134, 0, v80
	v_xor_b32_e32 v134, v134, v132
	v_add_u32_e32 v134, v133, v134
	v_add_u32_e32 v234, s90, v134
	v_add_u32_e32 v238, 0x22a00, v134
	v_or_b32_e32 v134, 32, v80
	v_xor_b32_e32 v134, v134, v132
	v_add_u32_e32 v134, v133, v134
	v_add_u32_e32 v235, s90, v134
	v_add_u32_e32 v239, 0x22a00, v134
	v_or_b32_e32 v134, 64, v80
	v_xor_b32_e32 v134, v134, v132
	v_add_u32_e32 v134, v133, v134
	v_add_u32_e32 v236, s90, v134
	v_add_u32_e32 v151, 0x22a00, v134
	v_or_b32_e32 v134, 96, v80
	v_xor_b32_e32 v134, v134, v132
	v_add_u32_e32 v134, v133, v134
	v_add_u32_e32 v237, s90, v134
	v_add_u32_e32 v176, 0x22a00, v134
	s_barrier
	v_and_b32_e32 v1, 15, v76
	v_lshl_add_u32 v0, v1, 5, 0
	v_add_u32_e32 v1, 0x22800, v0
	v_add_u32_e32 v0, 0x22000, v0
	ds_read_b128 v[98:101], v0 offset:16
	s_waitcnt lgkmcnt(0)
	v_cvt_pk_f16_f32 v87, v98, v99
	v_cvt_pk_f16_f32 v89, v100, v101
	ds_read_b128 v[98:101], v1
	s_waitcnt lgkmcnt(0)
	v_cvt_pk_f16_f32 v82, v98, v99
	v_cvt_pk_f16_f32 v84, v100, v101
	ds_read_b128 v[98:101], v0
	s_waitcnt lgkmcnt(0)
	v_cvt_pk_f16_f32 v83, v98, v99
	v_cvt_pk_f16_f32 v85, v100, v101
	ds_read_b128 v[98:101], v1 offset:16
	s_waitcnt lgkmcnt(0)
	v_cvt_pk_f16_f32 v86, v98, v99
	v_cvt_pk_f16_f32 v88, v100, v101
	ds_read_b128 v[98:101], v0 offset:528
	s_waitcnt lgkmcnt(0)
	v_cvt_pk_f16_f32 v91, v98, v99
	v_cvt_pk_f16_f32 v90, v100, v101
	ds_read_b128 v[98:101], v0 offset:512
	s_waitcnt lgkmcnt(0)
	v_cvt_pk_f16_f32 v93, v98, v99
	v_cvt_pk_f16_f32 v92, v100, v101
	ds_read_b128 v[98:101], v0 offset:1024
	s_waitcnt lgkmcnt(0)
	v_cvt_pk_f16_f32 v94, v98, v99
	v_cvt_pk_f16_f32 v95, v100, v101
	ds_read_b128 v[98:101], v0 offset:1040
	s_waitcnt lgkmcnt(0)
	v_cvt_pk_f16_f32 v96, v98, v99
	v_cvt_pk_f16_f32 v97, v100, v101
	ds_read_b128 v[98:101], v0 offset:1536
	s_waitcnt lgkmcnt(0)
	v_cvt_pk_f16_f32 v100, v100, v101
	v_cvt_pk_f16_f32 v101, v98, v99
	ds_read_b64 v[98:99], v0 offset:1552
	ds_read_b64 v[102:103], v0 offset:1560
	s_waitcnt lgkmcnt(0)
	v_cvt_pk_f16_f32 v99, v98, v99
	v_cvt_pk_f16_f32 v98, v102, v103
	s_branch .LBB0_361

.LBB0_361:
	v_mov_b32_e32 v115, v76
	s_lshl_b32 s52, s24, 8
	v_and_b32_e32 v1, 15, v115
	s_waitcnt lgkmcnt(0)
	v_ashrrev_i32_e32 v114, 1, v115
	v_pk_fma_f16 v2, v83, v32, v82
	v_pk_fma_f16 v3, v85, v33, v84
	v_pk_fma_f16 v4, v87, v34, v86
	v_pk_fma_f16 v5, v89, v35, v88
	v_and_b32_e32 v0, -8, v114
	v_pk_fma_f16 v5, v90, v39, v5
	v_pk_fma_f16 v4, v91, v38, v4
	v_pk_fma_f16 v3, v92, v37, v3
	v_pk_fma_f16 v2, v93, v36, v2
	v_pk_fma_f16 v6, v83, v36, v82
	v_pk_fma_f16 v7, v85, v37, v84
	v_pk_fma_f16 v8, v87, v38, v86
	v_pk_fma_f16 v9, v89, v39, v88
	v_lshlrev_b32_e32 v1, 4, v1
	v_pk_fma_f16 v2, v94, v40, v2
	v_pk_fma_f16 v3, v95, v41, v3
	v_pk_fma_f16 v4, v96, v42, v4
	v_pk_fma_f16 v5, v97, v43, v5
	v_pk_fma_f16 v9, v90, v43, v9
	v_pk_fma_f16 v8, v91, v42, v8
	v_pk_fma_f16 v7, v92, v41, v7
	v_pk_fma_f16 v6, v93, v40, v6
	v_pk_fma_f16 v10, v83, v40, v82
	v_pk_fma_f16 v11, v85, v41, v84
	v_pk_fma_f16 v12, v87, v42, v86
	v_pk_fma_f16 v13, v89, v43, v88
	v_lshl_add_u32 v132, v0, 8, 0
	v_pk_fma_f16 v5, v98, v47, v5
	v_pk_fma_f16 v4, v99, v46, v4
	v_pk_fma_f16 v3, v100, v45, v3
	v_pk_fma_f16 v2, v101, v44, v2
	v_pk_fma_f16 v6, v94, v44, v6
	v_pk_fma_f16 v7, v95, v45, v7
	v_pk_fma_f16 v8, v96, v46, v8
	v_pk_fma_f16 v9, v97, v47, v9
	v_pk_fma_f16 v13, v90, v47, v13
	v_pk_fma_f16 v12, v91, v46, v12
	v_pk_fma_f16 v11, v92, v45, v11
	v_pk_fma_f16 v10, v93, v44, v10
	v_pk_fma_f16 v14, v83, v44, v82
	v_pk_fma_f16 v15, v85, v45, v84
	v_pk_fma_f16 v16, v87, v46, v86
	v_pk_fma_f16 v17, v89, v47, v88
	v_add_u32_e32 v133, v132, v1
	v_pk_fma_f16 v9, v98, v51, v9
	v_pk_fma_f16 v8, v99, v50, v8
	v_pk_fma_f16 v7, v100, v49, v7
	v_pk_fma_f16 v6, v101, v48, v6
	v_pk_fma_f16 v10, v94, v48, v10
	v_pk_fma_f16 v11, v95, v49, v11
	v_pk_fma_f16 v12, v96, v50, v12
	v_pk_fma_f16 v13, v97, v51, v13
	v_pk_fma_f16 v17, v90, v51, v17
	v_pk_fma_f16 v16, v91, v50, v16
	v_pk_fma_f16 v15, v92, v49, v15
	v_pk_fma_f16 v14, v93, v48, v14
	ds_write_b128 v133, v[2:5]
	v_xad_u32 v2, v1, 16, v132
	v_pk_fma_f16 v13, v98, v55, v13
	v_pk_fma_f16 v12, v99, v54, v12
	v_pk_fma_f16 v11, v100, v53, v11
	v_pk_fma_f16 v10, v101, v52, v10
	v_pk_fma_f16 v14, v94, v52, v14
	v_pk_fma_f16 v15, v95, v53, v15
	v_pk_fma_f16 v16, v96, v54, v16
	v_pk_fma_f16 v17, v97, v55, v17
	ds_write_b128 v2, v[6:9] offset:256
	v_xad_u32 v2, v1, 32, v132
	v_pk_fma_f16 v17, v98, v59, v17
	v_pk_fma_f16 v16, v99, v58, v16
	v_pk_fma_f16 v15, v100, v57, v15
	v_pk_fma_f16 v14, v101, v56, v14
	ds_write_b128 v2, v[10:13] offset:512
	v_xad_u32 v2, v1, 48, v132
	ds_write_b128 v2, v[14:17] offset:768
	v_pk_fma_f16 v2, v83, v48, v82
	v_pk_fma_f16 v3, v85, v49, v84
	v_pk_fma_f16 v4, v87, v50, v86
	v_pk_fma_f16 v5, v89, v51, v88
	v_pk_fma_f16 v4, v91, v54, v4
	v_pk_fma_f16 v5, v90, v55, v5
	v_pk_fma_f16 v3, v92, v53, v3
	v_pk_fma_f16 v2, v93, v52, v2
	v_pk_fma_f16 v6, v83, v52, v82
	v_pk_fma_f16 v7, v85, v53, v84
	v_pk_fma_f16 v8, v87, v54, v86
	v_pk_fma_f16 v9, v89, v55, v88
	v_pk_fma_f16 v10, v83, v56, v82
	v_pk_fma_f16 v14, v83, v60, v82
	v_pk_fma_f16 v2, v94, v56, v2
	v_pk_fma_f16 v3, v95, v57, v3
	v_pk_fma_f16 v4, v96, v58, v4
	v_pk_fma_f16 v5, v97, v59, v5
	v_pk_fma_f16 v9, v90, v59, v9
	v_pk_fma_f16 v8, v91, v58, v8
	v_pk_fma_f16 v7, v92, v57, v7
	v_pk_fma_f16 v6, v93, v56, v6
	v_pk_fma_f16 v11, v85, v57, v84
	v_pk_fma_f16 v12, v87, v58, v86
	v_pk_fma_f16 v13, v89, v59, v88
	v_pk_fma_f16 v10, v93, v60, v10
	v_pk_fma_f16 v14, v93, v64, v14
	v_pk_fma_f16 v5, v98, v63, v5
	v_pk_fma_f16 v4, v99, v62, v4
	v_pk_fma_f16 v3, v100, v61, v3
	v_pk_fma_f16 v2, v101, v60, v2
	v_pk_fma_f16 v6, v94, v60, v6
	v_pk_fma_f16 v7, v95, v61, v7
	v_pk_fma_f16 v8, v96, v62, v8
	v_pk_fma_f16 v9, v97, v63, v9
	v_pk_fma_f16 v13, v90, v63, v13
	v_pk_fma_f16 v12, v91, v62, v12
	v_pk_fma_f16 v11, v92, v61, v11
	v_pk_fma_f16 v10, v94, v64, v10
	v_pk_fma_f16 v14, v94, v68, v14
	v_xad_u32 v18, v1, 64, v132
	v_pk_fma_f16 v15, v85, v61, v84
	v_pk_fma_f16 v16, v87, v62, v86
	v_pk_fma_f16 v17, v89, v63, v88
	v_pk_fma_f16 v9, v98, v67, v9
	v_pk_fma_f16 v8, v99, v66, v8
	v_pk_fma_f16 v7, v100, v65, v7
	v_pk_fma_f16 v6, v101, v64, v6
	v_pk_fma_f16 v11, v95, v65, v11
	v_pk_fma_f16 v12, v96, v66, v12
	v_pk_fma_f16 v13, v97, v67, v13
	ds_write_b128 v18, v[2:5] offset:1024
	v_xad_u32 v2, v1, s82, v132
	v_pk_fma_f16 v17, v90, v67, v17
	v_pk_fma_f16 v16, v91, v66, v16
	v_pk_fma_f16 v15, v92, v65, v15
	v_pk_fma_f16 v13, v98, v71, v13
	v_pk_fma_f16 v12, v99, v70, v12
	v_pk_fma_f16 v11, v100, v69, v11
	v_pk_fma_f16 v10, v101, v68, v10
	ds_write_b128 v2, v[6:9] offset:1280
	v_xad_u32 v2, v1, s83, v132
	v_pk_fma_f16 v15, v95, v69, v15
	v_pk_fma_f16 v16, v96, v70, v16
	v_pk_fma_f16 v17, v97, v71, v17
	ds_write_b128 v2, v[10:13] offset:1536
	v_lshl_or_b32 v2, v114, 8, v130
	v_xor_b32_e32 v3, 0x70, v1
	v_pk_fma_f16 v17, v98, v75, v17
	v_pk_fma_f16 v16, v99, v74, v16
	v_pk_fma_f16 v15, v100, v73, v15
	v_pk_fma_f16 v14, v101, v72, v14
	v_add3_u32 v2, 0, v2, v3
	s_cmp_eq_u32 s24, 15
	ds_write_b128 v2, v[14:17]
	s_cbranch_scc1 .LBB0_363
	v_add_u32_e32 v0, s52, v0
	v_lshl_or_b32 v0, v0, 11, v1
	v_add_u32_e32 v1, 0x7e800, v0
	v_add_u32_e32 v2, 0x7f000, v0
	global_load_dwordx4 v[32:35], v1, s[20:21]
	global_load_dwordx4 v[36:39], v2, s[20:21]
	v_add_u32_e32 v1, 0x7f800, v0
	v_add_u32_e32 v2, 0x80000, v0
	global_load_dwordx4 v[40:43], v1, s[20:21]
	global_load_dwordx4 v[44:47], v2, s[20:21]
	v_add_u32_e32 v1, 0x80800, v0
	v_add_u32_e32 v2, 0x81000, v0
	global_load_dwordx4 v[48:51], v1, s[20:21]
	global_load_dwordx4 v[52:55], v2, s[20:21]
	v_add_u32_e32 v1, 0x81800, v0
	v_add_u32_e32 v2, 0x82000, v0
	global_load_dwordx4 v[56:59], v1, s[20:21]
	global_load_dwordx4 v[60:63], v2, s[20:21]
	v_add_u32_e32 v1, 0x82800, v0
	v_add_u32_e32 v2, 0x83000, v0
	v_add_u32_e32 v0, 0x83800, v0
	global_load_dwordx4 v[64:67], v1, s[20:21]
	global_load_dwordx4 v[68:71], v2, s[20:21]
	global_load_dwordx4 v[72:75], v0, s[20:21]
